# vidpp: scanner loads vi for 32 steps as 2 dwords per lane per chunk and row-broadcasts it per step with DPP (row_newbcast) instead of an LDS read per 2 steps
# baseline (speedup 1.0000x reference)
.LBB0_726:
	s_and_b32 s1, s0, 1
	s_lshl_b32 s31, s1, 8
	s_mul_i32 s30, s1, 0xa000
	s_add_i32 s31, s31, 0x18000
	v_add_u32_e32 v6, s30, v151
	v_mov_b32_e32 v8, s31
	v_lshl_add_u32 v7, s1, 13, v0
	v_lshl_add_u32 v9, s1, 11, v39
	v_add_u32_e32 v22, 0x400, v9
	v_and_b32_e32 v28, 15, v170
	v_lshl_add_u32 v28, v28, 8, v7
	ds_read2st64_b32 v[24:25], v28 offset1:16
	ds_read_b128 v[58:61], v6
	ds_read_b128 v[62:65], v6 offset:16
	ds_read_b128 v[66:69], v6 offset:32
	ds_read_b128 v[70:73], v6 offset:48
	ds_read_b128 v[74:77], v6 offset:64
	ds_read_b64 v[120:121], v8
	ds_read_b128 v[78:81], v6 offset:1280
	ds_read_b128 v[82:85], v6 offset:1296
	ds_read_b128 v[86:89], v6 offset:1312
	ds_read_b128 v[90:93], v6 offset:1328
	ds_read_b128 v[94:97], v6 offset:1344
	s_waitcnt lgkmcnt(11)
	v_mov_b32_dpp v26, v24 row_newbcast:0 row_mask:0xf bank_mask:0xf
	ds_read_b128 v[98:101], v6 offset:2560
	ds_read_b128 v[102:105], v6 offset:2576
	ds_read_b128 v[106:109], v6 offset:2592
	ds_read_b128 v[110:113], v6 offset:2608
	ds_read_b128 v[114:117], v6 offset:2624
	ds_read_b64 v[208:209], v8 offset:8
	s_waitcnt lgkmcnt(11)
	v_pk_mul_f32 v[10:11], v[2:3], v[58:59] op_sel_hi:[0,1]
	v_pk_fma_f32 v[10:11], v[2:3], v[60:61], v[10:11] op_sel:[1,0,0] op_sel_hi:[1,1,1]
	v_pk_fma_f32 v[10:11], v[4:5], v[62:63], v[10:11] op_sel_hi:[0,1,1]
	v_pk_fma_f32 v[10:11], v[4:5], v[64:65], v[10:11] op_sel:[1,0,0] op_sel_hi:[1,1,1]
	v_pk_mul_f32 v[18:19], v[74:75], v[26:27] op_sel_hi:[1,0]
	v_pk_mul_f32 v[20:21], v[76:77], v[26:27] op_sel_hi:[1,0]
	v_add_f32_dpp v10, v10, v10 quad_perm:[1,0,3,2] row_mask:0xf bank_mask:0xf bound_ctrl:1
	v_add_f32_dpp v11, v11, v11 quad_perm:[1,0,3,2] row_mask:0xf bank_mask:0xf bound_ctrl:1
	v_pk_fma_f32 v[18:19], v[2:3], v[66:67], v[18:19]
	v_add_f32_dpp v10, v10, v10 quad_perm:[2,3,0,1] row_mask:0xf bank_mask:0xf bound_ctrl:1
	v_add_f32_dpp v11, v11, v11 quad_perm:[2,3,0,1] row_mask:0xf bank_mask:0xf bound_ctrl:1
	v_pk_fma_f32 v[20:21], v[4:5], v[68:69], v[20:21]
	v_add_f32_dpp v10, v10, v10 row_half_mirror row_mask:0xf bank_mask:0xf bound_ctrl:1
	v_add_f32_dpp v11, v11, v11 row_half_mirror row_mask:0xf bank_mask:0xf bound_ctrl:1
	s_nop 0
	v_add_f32_dpp v10, v10, v10 row_mirror row_mask:0xf bank_mask:0xf bound_ctrl:1
	v_add_f32_dpp v11, v11, v11 row_mirror row_mask:0xf bank_mask:0xf bound_ctrl:1
	v_pk_fma_f32 v[2:3], v[70:71], v[10:11], v[18:19] op_sel_hi:[1,0,1]
	v_pk_fma_f32 v[4:5], v[72:73], v[10:11], v[20:21] op_sel_hi:[1,0,1]
	v_mov_b32_dpp v26, v24 row_newbcast:1 row_mask:0xf bank_mask:0xf
	v_fmac_f32_e32 v11, v120, v10
	ds_read_b128 v[186:189], v6 offset:3840
	ds_read_b128 v[190:193], v6 offset:3856
	ds_read_b128 v[194:197], v6 offset:3872
	ds_read_b128 v[198:201], v6 offset:3888
	ds_read_b128 v[202:205], v6 offset:3904
	s_waitcnt lgkmcnt(11)
	v_pk_mul_f32 v[12:13], v[2:3], v[78:79] op_sel_hi:[0,1]
	v_pk_fma_f32 v[12:13], v[2:3], v[80:81], v[12:13] op_sel:[1,0,0] op_sel_hi:[1,1,1]
	v_pk_fma_f32 v[12:13], v[4:5], v[82:83], v[12:13] op_sel_hi:[0,1,1]
	v_pk_fma_f32 v[12:13], v[4:5], v[84:85], v[12:13] op_sel:[1,0,0] op_sel_hi:[1,1,1]
	v_pk_mul_f32 v[18:19], v[94:95], v[26:27] op_sel_hi:[1,0]
	v_pk_mul_f32 v[20:21], v[96:97], v[26:27] op_sel_hi:[1,0]
	v_add_f32_dpp v12, v12, v12 quad_perm:[1,0,3,2] row_mask:0xf bank_mask:0xf bound_ctrl:1
	v_add_f32_dpp v13, v13, v13 quad_perm:[1,0,3,2] row_mask:0xf bank_mask:0xf bound_ctrl:1
	v_pk_fma_f32 v[18:19], v[2:3], v[86:87], v[18:19]
	v_add_f32_dpp v12, v12, v12 quad_perm:[2,3,0,1] row_mask:0xf bank_mask:0xf bound_ctrl:1
	v_add_f32_dpp v13, v13, v13 quad_perm:[2,3,0,1] row_mask:0xf bank_mask:0xf bound_ctrl:1
	v_pk_fma_f32 v[20:21], v[4:5], v[88:89], v[20:21]
	v_add_f32_dpp v12, v12, v12 row_half_mirror row_mask:0xf bank_mask:0xf bound_ctrl:1
	v_add_f32_dpp v13, v13, v13 row_half_mirror row_mask:0xf bank_mask:0xf bound_ctrl:1
	s_nop 0
	v_add_f32_dpp v12, v12, v12 row_mirror row_mask:0xf bank_mask:0xf bound_ctrl:1
	v_add_f32_dpp v13, v13, v13 row_mirror row_mask:0xf bank_mask:0xf bound_ctrl:1
	v_pk_fma_f32 v[2:3], v[90:91], v[12:13], v[18:19] op_sel_hi:[1,0,1]
	v_pk_fma_f32 v[4:5], v[92:93], v[12:13], v[20:21] op_sel_hi:[1,0,1]
	v_mov_b32_dpp v26, v24 row_newbcast:2 row_mask:0xf bank_mask:0xf
	v_fmac_f32_e32 v13, v121, v12
	ds_write2_b32 v9, v11, v13 offset1:16
	ds_read_b128 v[58:61], v6 offset:5120
	ds_read_b128 v[62:65], v6 offset:5136
	ds_read_b128 v[66:69], v6 offset:5152
	ds_read_b128 v[70:73], v6 offset:5168
	ds_read_b128 v[74:77], v6 offset:5184
	ds_read_b64 v[120:121], v8 offset:16
	s_waitcnt lgkmcnt(12)
	v_pk_mul_f32 v[14:15], v[2:3], v[98:99] op_sel_hi:[0,1]
	v_pk_fma_f32 v[14:15], v[2:3], v[100:101], v[14:15] op_sel:[1,0,0] op_sel_hi:[1,1,1]
	v_pk_fma_f32 v[14:15], v[4:5], v[102:103], v[14:15] op_sel_hi:[0,1,1]
	v_pk_fma_f32 v[14:15], v[4:5], v[104:105], v[14:15] op_sel:[1,0,0] op_sel_hi:[1,1,1]
	v_pk_mul_f32 v[18:19], v[114:115], v[26:27] op_sel_hi:[1,0]
	v_pk_mul_f32 v[20:21], v[116:117], v[26:27] op_sel_hi:[1,0]
	v_add_f32_dpp v14, v14, v14 quad_perm:[1,0,3,2] row_mask:0xf bank_mask:0xf bound_ctrl:1
	v_add_f32_dpp v15, v15, v15 quad_perm:[1,0,3,2] row_mask:0xf bank_mask:0xf bound_ctrl:1
	v_pk_fma_f32 v[18:19], v[2:3], v[106:107], v[18:19]
	v_add_f32_dpp v14, v14, v14 quad_perm:[2,3,0,1] row_mask:0xf bank_mask:0xf bound_ctrl:1
	v_add_f32_dpp v15, v15, v15 quad_perm:[2,3,0,1] row_mask:0xf bank_mask:0xf bound_ctrl:1
	v_pk_fma_f32 v[20:21], v[4:5], v[108:109], v[20:21]
	v_add_f32_dpp v14, v14, v14 row_half_mirror row_mask:0xf bank_mask:0xf bound_ctrl:1
	v_add_f32_dpp v15, v15, v15 row_half_mirror row_mask:0xf bank_mask:0xf bound_ctrl:1
	s_nop 0
	v_add_f32_dpp v14, v14, v14 row_mirror row_mask:0xf bank_mask:0xf bound_ctrl:1
	v_add_f32_dpp v15, v15, v15 row_mirror row_mask:0xf bank_mask:0xf bound_ctrl:1
	v_pk_fma_f32 v[2:3], v[110:111], v[14:15], v[18:19] op_sel_hi:[1,0,1]
	v_pk_fma_f32 v[4:5], v[112:113], v[14:15], v[20:21] op_sel_hi:[1,0,1]
	v_mov_b32_dpp v26, v24 row_newbcast:3 row_mask:0xf bank_mask:0xf
	v_fmac_f32_e32 v15, v208, v14
	ds_read_b128 v[78:81], v6 offset:6400
	ds_read_b128 v[82:85], v6 offset:6416
	ds_read_b128 v[86:89], v6 offset:6432
	ds_read_b128 v[90:93], v6 offset:6448
	ds_read_b128 v[94:97], v6 offset:6464
	s_waitcnt lgkmcnt(12)
	v_pk_mul_f32 v[16:17], v[2:3], v[186:187] op_sel_hi:[0,1]
	v_pk_fma_f32 v[16:17], v[2:3], v[188:189], v[16:17] op_sel:[1,0,0] op_sel_hi:[1,1,1]
	v_pk_fma_f32 v[16:17], v[4:5], v[190:191], v[16:17] op_sel_hi:[0,1,1]
	v_pk_fma_f32 v[16:17], v[4:5], v[192:193], v[16:17] op_sel:[1,0,0] op_sel_hi:[1,1,1]
	v_pk_mul_f32 v[18:19], v[202:203], v[26:27] op_sel_hi:[1,0]
	v_pk_mul_f32 v[20:21], v[204:205], v[26:27] op_sel_hi:[1,0]
	v_add_f32_dpp v16, v16, v16 quad_perm:[1,0,3,2] row_mask:0xf bank_mask:0xf bound_ctrl:1
	v_add_f32_dpp v17, v17, v17 quad_perm:[1,0,3,2] row_mask:0xf bank_mask:0xf bound_ctrl:1
	v_pk_fma_f32 v[18:19], v[2:3], v[194:195], v[18:19]
	v_add_f32_dpp v16, v16, v16 quad_perm:[2,3,0,1] row_mask:0xf bank_mask:0xf bound_ctrl:1
	v_add_f32_dpp v17, v17, v17 quad_perm:[2,3,0,1] row_mask:0xf bank_mask:0xf bound_ctrl:1
	v_pk_fma_f32 v[20:21], v[4:5], v[196:197], v[20:21]
	v_add_f32_dpp v16, v16, v16 row_half_mirror row_mask:0xf bank_mask:0xf bound_ctrl:1
	v_add_f32_dpp v17, v17, v17 row_half_mirror row_mask:0xf bank_mask:0xf bound_ctrl:1
	s_nop 0
	v_add_f32_dpp v16, v16, v16 row_mirror row_mask:0xf bank_mask:0xf bound_ctrl:1
	v_add_f32_dpp v17, v17, v17 row_mirror row_mask:0xf bank_mask:0xf bound_ctrl:1
	v_pk_fma_f32 v[2:3], v[198:199], v[16:17], v[18:19] op_sel_hi:[1,0,1]
	v_pk_fma_f32 v[4:5], v[200:201], v[16:17], v[20:21] op_sel_hi:[1,0,1]
	v_mov_b32_dpp v26, v24 row_newbcast:4 row_mask:0xf bank_mask:0xf
	v_fmac_f32_e32 v17, v209, v16
	ds_write2_b32 v9, v15, v17 offset0:32 offset1:48
	ds_read_b128 v[98:101], v6 offset:7680
	ds_read_b128 v[102:105], v6 offset:7696
	ds_read_b128 v[106:109], v6 offset:7712
	ds_read_b128 v[110:113], v6 offset:7728
	ds_read_b128 v[114:117], v6 offset:7744
	ds_read_b64 v[208:209], v8 offset:24
	s_waitcnt lgkmcnt(12)
	v_pk_mul_f32 v[10:11], v[2:3], v[58:59] op_sel_hi:[0,1]
	v_pk_fma_f32 v[10:11], v[2:3], v[60:61], v[10:11] op_sel:[1,0,0] op_sel_hi:[1,1,1]
	v_pk_fma_f32 v[10:11], v[4:5], v[62:63], v[10:11] op_sel_hi:[0,1,1]
	v_pk_fma_f32 v[10:11], v[4:5], v[64:65], v[10:11] op_sel:[1,0,0] op_sel_hi:[1,1,1]
	v_pk_mul_f32 v[18:19], v[74:75], v[26:27] op_sel_hi:[1,0]
	v_pk_mul_f32 v[20:21], v[76:77], v[26:27] op_sel_hi:[1,0]
	v_add_f32_dpp v10, v10, v10 quad_perm:[1,0,3,2] row_mask:0xf bank_mask:0xf bound_ctrl:1
	v_add_f32_dpp v11, v11, v11 quad_perm:[1,0,3,2] row_mask:0xf bank_mask:0xf bound_ctrl:1
	v_pk_fma_f32 v[18:19], v[2:3], v[66:67], v[18:19]
	v_add_f32_dpp v10, v10, v10 quad_perm:[2,3,0,1] row_mask:0xf bank_mask:0xf bound_ctrl:1
	v_add_f32_dpp v11, v11, v11 quad_perm:[2,3,0,1] row_mask:0xf bank_mask:0xf bound_ctrl:1
	v_pk_fma_f32 v[20:21], v[4:5], v[68:69], v[20:21]
	v_add_f32_dpp v10, v10, v10 row_half_mirror row_mask:0xf bank_mask:0xf bound_ctrl:1
	v_add_f32_dpp v11, v11, v11 row_half_mirror row_mask:0xf bank_mask:0xf bound_ctrl:1
	s_nop 0
	v_add_f32_dpp v10, v10, v10 row_mirror row_mask:0xf bank_mask:0xf bound_ctrl:1
	v_add_f32_dpp v11, v11, v11 row_mirror row_mask:0xf bank_mask:0xf bound_ctrl:1
	v_pk_fma_f32 v[2:3], v[70:71], v[10:11], v[18:19] op_sel_hi:[1,0,1]
	v_pk_fma_f32 v[4:5], v[72:73], v[10:11], v[20:21] op_sel_hi:[1,0,1]
	v_mov_b32_dpp v26, v24 row_newbcast:5 row_mask:0xf bank_mask:0xf
	v_fmac_f32_e32 v11, v120, v10
	ds_read_b128 v[186:189], v6 offset:8960
	ds_read_b128 v[190:193], v6 offset:8976
	ds_read_b128 v[194:197], v6 offset:8992
	ds_read_b128 v[198:201], v6 offset:9008
	ds_read_b128 v[202:205], v6 offset:9024
	s_waitcnt lgkmcnt(12)
	v_pk_mul_f32 v[12:13], v[2:3], v[78:79] op_sel_hi:[0,1]
	v_pk_fma_f32 v[12:13], v[2:3], v[80:81], v[12:13] op_sel:[1,0,0] op_sel_hi:[1,1,1]
	v_pk_fma_f32 v[12:13], v[4:5], v[82:83], v[12:13] op_sel_hi:[0,1,1]
	v_pk_fma_f32 v[12:13], v[4:5], v[84:85], v[12:13] op_sel:[1,0,0] op_sel_hi:[1,1,1]
	v_pk_mul_f32 v[18:19], v[94:95], v[26:27] op_sel_hi:[1,0]
	v_pk_mul_f32 v[20:21], v[96:97], v[26:27] op_sel_hi:[1,0]
	v_add_f32_dpp v12, v12, v12 quad_perm:[1,0,3,2] row_mask:0xf bank_mask:0xf bound_ctrl:1
	v_add_f32_dpp v13, v13, v13 quad_perm:[1,0,3,2] row_mask:0xf bank_mask:0xf bound_ctrl:1
	v_pk_fma_f32 v[18:19], v[2:3], v[86:87], v[18:19]
	v_add_f32_dpp v12, v12, v12 quad_perm:[2,3,0,1] row_mask:0xf bank_mask:0xf bound_ctrl:1
	v_add_f32_dpp v13, v13, v13 quad_perm:[2,3,0,1] row_mask:0xf bank_mask:0xf bound_ctrl:1
	v_pk_fma_f32 v[20:21], v[4:5], v[88:89], v[20:21]
	v_add_f32_dpp v12, v12, v12 row_half_mirror row_mask:0xf bank_mask:0xf bound_ctrl:1
	v_add_f32_dpp v13, v13, v13 row_half_mirror row_mask:0xf bank_mask:0xf bound_ctrl:1
	s_nop 0
	v_add_f32_dpp v12, v12, v12 row_mirror row_mask:0xf bank_mask:0xf bound_ctrl:1
	v_add_f32_dpp v13, v13, v13 row_mirror row_mask:0xf bank_mask:0xf bound_ctrl:1
	v_pk_fma_f32 v[2:3], v[90:91], v[12:13], v[18:19] op_sel_hi:[1,0,1]
	v_pk_fma_f32 v[4:5], v[92:93], v[12:13], v[20:21] op_sel_hi:[1,0,1]
	v_mov_b32_dpp v26, v24 row_newbcast:6 row_mask:0xf bank_mask:0xf
	v_fmac_f32_e32 v13, v121, v12
	ds_write2_b32 v9, v11, v13 offset0:64 offset1:80
	ds_read_b128 v[58:61], v6 offset:10240
	ds_read_b128 v[62:65], v6 offset:10256
	ds_read_b128 v[66:69], v6 offset:10272
	ds_read_b128 v[70:73], v6 offset:10288
	ds_read_b128 v[74:77], v6 offset:10304
	ds_read_b64 v[120:121], v8 offset:32
	s_waitcnt lgkmcnt(12)
	v_pk_mul_f32 v[14:15], v[2:3], v[98:99] op_sel_hi:[0,1]
	v_pk_fma_f32 v[14:15], v[2:3], v[100:101], v[14:15] op_sel:[1,0,0] op_sel_hi:[1,1,1]
	v_pk_fma_f32 v[14:15], v[4:5], v[102:103], v[14:15] op_sel_hi:[0,1,1]
	v_pk_fma_f32 v[14:15], v[4:5], v[104:105], v[14:15] op_sel:[1,0,0] op_sel_hi:[1,1,1]
	v_pk_mul_f32 v[18:19], v[114:115], v[26:27] op_sel_hi:[1,0]
	v_pk_mul_f32 v[20:21], v[116:117], v[26:27] op_sel_hi:[1,0]
	v_add_f32_dpp v14, v14, v14 quad_perm:[1,0,3,2] row_mask:0xf bank_mask:0xf bound_ctrl:1
	v_add_f32_dpp v15, v15, v15 quad_perm:[1,0,3,2] row_mask:0xf bank_mask:0xf bound_ctrl:1
	v_pk_fma_f32 v[18:19], v[2:3], v[106:107], v[18:19]
	v_add_f32_dpp v14, v14, v14 quad_perm:[2,3,0,1] row_mask:0xf bank_mask:0xf bound_ctrl:1
	v_add_f32_dpp v15, v15, v15 quad_perm:[2,3,0,1] row_mask:0xf bank_mask:0xf bound_ctrl:1
	v_pk_fma_f32 v[20:21], v[4:5], v[108:109], v[20:21]
	v_add_f32_dpp v14, v14, v14 row_half_mirror row_mask:0xf bank_mask:0xf bound_ctrl:1
	v_add_f32_dpp v15, v15, v15 row_half_mirror row_mask:0xf bank_mask:0xf bound_ctrl:1
	s_nop 0
	v_add_f32_dpp v14, v14, v14 row_mirror row_mask:0xf bank_mask:0xf bound_ctrl:1
	v_add_f32_dpp v15, v15, v15 row_mirror row_mask:0xf bank_mask:0xf bound_ctrl:1
	v_pk_fma_f32 v[2:3], v[110:111], v[14:15], v[18:19] op_sel_hi:[1,0,1]
	v_pk_fma_f32 v[4:5], v[112:113], v[14:15], v[20:21] op_sel_hi:[1,0,1]
	v_mov_b32_dpp v26, v24 row_newbcast:7 row_mask:0xf bank_mask:0xf
	v_fmac_f32_e32 v15, v208, v14
	ds_read_b128 v[78:81], v6 offset:11520
	ds_read_b128 v[82:85], v6 offset:11536
	ds_read_b128 v[86:89], v6 offset:11552
	ds_read_b128 v[90:93], v6 offset:11568
	ds_read_b128 v[94:97], v6 offset:11584
	s_waitcnt lgkmcnt(12)
	v_pk_mul_f32 v[16:17], v[2:3], v[186:187] op_sel_hi:[0,1]
	v_pk_fma_f32 v[16:17], v[2:3], v[188:189], v[16:17] op_sel:[1,0,0] op_sel_hi:[1,1,1]
	v_pk_fma_f32 v[16:17], v[4:5], v[190:191], v[16:17] op_sel_hi:[0,1,1]
	v_pk_fma_f32 v[16:17], v[4:5], v[192:193], v[16:17] op_sel:[1,0,0] op_sel_hi:[1,1,1]
	v_pk_mul_f32 v[18:19], v[202:203], v[26:27] op_sel_hi:[1,0]
	v_pk_mul_f32 v[20:21], v[204:205], v[26:27] op_sel_hi:[1,0]
	v_add_f32_dpp v16, v16, v16 quad_perm:[1,0,3,2] row_mask:0xf bank_mask:0xf bound_ctrl:1
	v_add_f32_dpp v17, v17, v17 quad_perm:[1,0,3,2] row_mask:0xf bank_mask:0xf bound_ctrl:1
	v_pk_fma_f32 v[18:19], v[2:3], v[194:195], v[18:19]
	v_add_f32_dpp v16, v16, v16 quad_perm:[2,3,0,1] row_mask:0xf bank_mask:0xf bound_ctrl:1
	v_add_f32_dpp v17, v17, v17 quad_perm:[2,3,0,1] row_mask:0xf bank_mask:0xf bound_ctrl:1
	v_pk_fma_f32 v[20:21], v[4:5], v[196:197], v[20:21]
	v_add_f32_dpp v16, v16, v16 row_half_mirror row_mask:0xf bank_mask:0xf bound_ctrl:1
	v_add_f32_dpp v17, v17, v17 row_half_mirror row_mask:0xf bank_mask:0xf bound_ctrl:1
	s_nop 0
	v_add_f32_dpp v16, v16, v16 row_mirror row_mask:0xf bank_mask:0xf bound_ctrl:1
	v_add_f32_dpp v17, v17, v17 row_mirror row_mask:0xf bank_mask:0xf bound_ctrl:1
	v_pk_fma_f32 v[2:3], v[198:199], v[16:17], v[18:19] op_sel_hi:[1,0,1]
	v_pk_fma_f32 v[4:5], v[200:201], v[16:17], v[20:21] op_sel_hi:[1,0,1]
	v_mov_b32_dpp v26, v24 row_newbcast:8 row_mask:0xf bank_mask:0xf
	v_fmac_f32_e32 v17, v209, v16
	ds_write2_b32 v9, v15, v17 offset0:96 offset1:112
	ds_read_b128 v[98:101], v6 offset:12800
	ds_read_b128 v[102:105], v6 offset:12816
	ds_read_b128 v[106:109], v6 offset:12832
	ds_read_b128 v[110:113], v6 offset:12848
	ds_read_b128 v[114:117], v6 offset:12864
	ds_read_b64 v[208:209], v8 offset:40
	s_waitcnt lgkmcnt(12)
	v_pk_mul_f32 v[10:11], v[2:3], v[58:59] op_sel_hi:[0,1]
	v_pk_fma_f32 v[10:11], v[2:3], v[60:61], v[10:11] op_sel:[1,0,0] op_sel_hi:[1,1,1]
	v_pk_fma_f32 v[10:11], v[4:5], v[62:63], v[10:11] op_sel_hi:[0,1,1]
	v_pk_fma_f32 v[10:11], v[4:5], v[64:65], v[10:11] op_sel:[1,0,0] op_sel_hi:[1,1,1]
	v_pk_mul_f32 v[18:19], v[74:75], v[26:27] op_sel_hi:[1,0]
	v_pk_mul_f32 v[20:21], v[76:77], v[26:27] op_sel_hi:[1,0]
	v_add_f32_dpp v10, v10, v10 quad_perm:[1,0,3,2] row_mask:0xf bank_mask:0xf bound_ctrl:1
	v_add_f32_dpp v11, v11, v11 quad_perm:[1,0,3,2] row_mask:0xf bank_mask:0xf bound_ctrl:1
	v_pk_fma_f32 v[18:19], v[2:3], v[66:67], v[18:19]
	v_add_f32_dpp v10, v10, v10 quad_perm:[2,3,0,1] row_mask:0xf bank_mask:0xf bound_ctrl:1
	v_add_f32_dpp v11, v11, v11 quad_perm:[2,3,0,1] row_mask:0xf bank_mask:0xf bound_ctrl:1
	v_pk_fma_f32 v[20:21], v[4:5], v[68:69], v[20:21]
	v_add_f32_dpp v10, v10, v10 row_half_mirror row_mask:0xf bank_mask:0xf bound_ctrl:1
	v_add_f32_dpp v11, v11, v11 row_half_mirror row_mask:0xf bank_mask:0xf bound_ctrl:1
	s_nop 0
	v_add_f32_dpp v10, v10, v10 row_mirror row_mask:0xf bank_mask:0xf bound_ctrl:1
	v_add_f32_dpp v11, v11, v11 row_mirror row_mask:0xf bank_mask:0xf bound_ctrl:1
	v_pk_fma_f32 v[2:3], v[70:71], v[10:11], v[18:19] op_sel_hi:[1,0,1]
	v_pk_fma_f32 v[4:5], v[72:73], v[10:11], v[20:21] op_sel_hi:[1,0,1]
	v_mov_b32_dpp v26, v24 row_newbcast:9 row_mask:0xf bank_mask:0xf
	v_fmac_f32_e32 v11, v120, v10
	ds_read_b128 v[186:189], v6 offset:14080
	ds_read_b128 v[190:193], v6 offset:14096
	ds_read_b128 v[194:197], v6 offset:14112
	ds_read_b128 v[198:201], v6 offset:14128
	ds_read_b128 v[202:205], v6 offset:14144
	s_waitcnt lgkmcnt(12)
	v_pk_mul_f32 v[12:13], v[2:3], v[78:79] op_sel_hi:[0,1]
	v_pk_fma_f32 v[12:13], v[2:3], v[80:81], v[12:13] op_sel:[1,0,0] op_sel_hi:[1,1,1]
	v_pk_fma_f32 v[12:13], v[4:5], v[82:83], v[12:13] op_sel_hi:[0,1,1]
	v_pk_fma_f32 v[12:13], v[4:5], v[84:85], v[12:13] op_sel:[1,0,0] op_sel_hi:[1,1,1]
	v_pk_mul_f32 v[18:19], v[94:95], v[26:27] op_sel_hi:[1,0]
	v_pk_mul_f32 v[20:21], v[96:97], v[26:27] op_sel_hi:[1,0]
	v_add_f32_dpp v12, v12, v12 quad_perm:[1,0,3,2] row_mask:0xf bank_mask:0xf bound_ctrl:1
	v_add_f32_dpp v13, v13, v13 quad_perm:[1,0,3,2] row_mask:0xf bank_mask:0xf bound_ctrl:1
	v_pk_fma_f32 v[18:19], v[2:3], v[86:87], v[18:19]
	v_add_f32_dpp v12, v12, v12 quad_perm:[2,3,0,1] row_mask:0xf bank_mask:0xf bound_ctrl:1
	v_add_f32_dpp v13, v13, v13 quad_perm:[2,3,0,1] row_mask:0xf bank_mask:0xf bound_ctrl:1
	v_pk_fma_f32 v[20:21], v[4:5], v[88:89], v[20:21]
	v_add_f32_dpp v12, v12, v12 row_half_mirror row_mask:0xf bank_mask:0xf bound_ctrl:1
	v_add_f32_dpp v13, v13, v13 row_half_mirror row_mask:0xf bank_mask:0xf bound_ctrl:1
	s_nop 0
	v_add_f32_dpp v12, v12, v12 row_mirror row_mask:0xf bank_mask:0xf bound_ctrl:1
	v_add_f32_dpp v13, v13, v13 row_mirror row_mask:0xf bank_mask:0xf bound_ctrl:1
	v_pk_fma_f32 v[2:3], v[90:91], v[12:13], v[18:19] op_sel_hi:[1,0,1]
	v_pk_fma_f32 v[4:5], v[92:93], v[12:13], v[20:21] op_sel_hi:[1,0,1]
	v_mov_b32_dpp v26, v24 row_newbcast:10 row_mask:0xf bank_mask:0xf
	v_fmac_f32_e32 v13, v121, v12
	ds_write2_b32 v9, v11, v13 offset0:128 offset1:144
	ds_read_b128 v[58:61], v6 offset:15360
	ds_read_b128 v[62:65], v6 offset:15376
	ds_read_b128 v[66:69], v6 offset:15392
	ds_read_b128 v[70:73], v6 offset:15408
	ds_read_b128 v[74:77], v6 offset:15424
	ds_read_b64 v[120:121], v8 offset:48
	s_waitcnt lgkmcnt(12)
	v_pk_mul_f32 v[14:15], v[2:3], v[98:99] op_sel_hi:[0,1]
	v_pk_fma_f32 v[14:15], v[2:3], v[100:101], v[14:15] op_sel:[1,0,0] op_sel_hi:[1,1,1]
	v_pk_fma_f32 v[14:15], v[4:5], v[102:103], v[14:15] op_sel_hi:[0,1,1]
	v_pk_fma_f32 v[14:15], v[4:5], v[104:105], v[14:15] op_sel:[1,0,0] op_sel_hi:[1,1,1]
	v_pk_mul_f32 v[18:19], v[114:115], v[26:27] op_sel_hi:[1,0]
	v_pk_mul_f32 v[20:21], v[116:117], v[26:27] op_sel_hi:[1,0]
	v_add_f32_dpp v14, v14, v14 quad_perm:[1,0,3,2] row_mask:0xf bank_mask:0xf bound_ctrl:1
	v_add_f32_dpp v15, v15, v15 quad_perm:[1,0,3,2] row_mask:0xf bank_mask:0xf bound_ctrl:1
	v_pk_fma_f32 v[18:19], v[2:3], v[106:107], v[18:19]
	v_add_f32_dpp v14, v14, v14 quad_perm:[2,3,0,1] row_mask:0xf bank_mask:0xf bound_ctrl:1
	v_add_f32_dpp v15, v15, v15 quad_perm:[2,3,0,1] row_mask:0xf bank_mask:0xf bound_ctrl:1
	v_pk_fma_f32 v[20:21], v[4:5], v[108:109], v[20:21]
	v_add_f32_dpp v14, v14, v14 row_half_mirror row_mask:0xf bank_mask:0xf bound_ctrl:1
	v_add_f32_dpp v15, v15, v15 row_half_mirror row_mask:0xf bank_mask:0xf bound_ctrl:1
	s_nop 0
	v_add_f32_dpp v14, v14, v14 row_mirror row_mask:0xf bank_mask:0xf bound_ctrl:1
	v_add_f32_dpp v15, v15, v15 row_mirror row_mask:0xf bank_mask:0xf bound_ctrl:1
	v_pk_fma_f32 v[2:3], v[110:111], v[14:15], v[18:19] op_sel_hi:[1,0,1]
	v_pk_fma_f32 v[4:5], v[112:113], v[14:15], v[20:21] op_sel_hi:[1,0,1]
	v_mov_b32_dpp v26, v24 row_newbcast:11 row_mask:0xf bank_mask:0xf
	v_fmac_f32_e32 v15, v208, v14
	ds_read_b128 v[78:81], v6 offset:16640
	ds_read_b128 v[82:85], v6 offset:16656
	ds_read_b128 v[86:89], v6 offset:16672
	ds_read_b128 v[90:93], v6 offset:16688
	ds_read_b128 v[94:97], v6 offset:16704
	s_waitcnt lgkmcnt(12)
	v_pk_mul_f32 v[16:17], v[2:3], v[186:187] op_sel_hi:[0,1]
	v_pk_fma_f32 v[16:17], v[2:3], v[188:189], v[16:17] op_sel:[1,0,0] op_sel_hi:[1,1,1]
	v_pk_fma_f32 v[16:17], v[4:5], v[190:191], v[16:17] op_sel_hi:[0,1,1]
	v_pk_fma_f32 v[16:17], v[4:5], v[192:193], v[16:17] op_sel:[1,0,0] op_sel_hi:[1,1,1]
	v_pk_mul_f32 v[18:19], v[202:203], v[26:27] op_sel_hi:[1,0]
	v_pk_mul_f32 v[20:21], v[204:205], v[26:27] op_sel_hi:[1,0]
	v_add_f32_dpp v16, v16, v16 quad_perm:[1,0,3,2] row_mask:0xf bank_mask:0xf bound_ctrl:1
	v_add_f32_dpp v17, v17, v17 quad_perm:[1,0,3,2] row_mask:0xf bank_mask:0xf bound_ctrl:1
	v_pk_fma_f32 v[18:19], v[2:3], v[194:195], v[18:19]
	v_add_f32_dpp v16, v16, v16 quad_perm:[2,3,0,1] row_mask:0xf bank_mask:0xf bound_ctrl:1
	v_add_f32_dpp v17, v17, v17 quad_perm:[2,3,0,1] row_mask:0xf bank_mask:0xf bound_ctrl:1
	v_pk_fma_f32 v[20:21], v[4:5], v[196:197], v[20:21]
	v_add_f32_dpp v16, v16, v16 row_half_mirror row_mask:0xf bank_mask:0xf bound_ctrl:1
	v_add_f32_dpp v17, v17, v17 row_half_mirror row_mask:0xf bank_mask:0xf bound_ctrl:1
	s_nop 0
	v_add_f32_dpp v16, v16, v16 row_mirror row_mask:0xf bank_mask:0xf bound_ctrl:1
	v_add_f32_dpp v17, v17, v17 row_mirror row_mask:0xf bank_mask:0xf bound_ctrl:1
	v_pk_fma_f32 v[2:3], v[198:199], v[16:17], v[18:19] op_sel_hi:[1,0,1]
	v_pk_fma_f32 v[4:5], v[200:201], v[16:17], v[20:21] op_sel_hi:[1,0,1]
	v_mov_b32_dpp v26, v24 row_newbcast:12 row_mask:0xf bank_mask:0xf
	v_fmac_f32_e32 v17, v209, v16
	ds_write2_b32 v9, v15, v17 offset0:160 offset1:176
	ds_read_b128 v[98:101], v6 offset:17920
	ds_read_b128 v[102:105], v6 offset:17936
	ds_read_b128 v[106:109], v6 offset:17952
	ds_read_b128 v[110:113], v6 offset:17968
	ds_read_b128 v[114:117], v6 offset:17984
	ds_read_b64 v[208:209], v8 offset:56
	s_waitcnt lgkmcnt(12)
	v_pk_mul_f32 v[10:11], v[2:3], v[58:59] op_sel_hi:[0,1]
	v_pk_fma_f32 v[10:11], v[2:3], v[60:61], v[10:11] op_sel:[1,0,0] op_sel_hi:[1,1,1]
	v_pk_fma_f32 v[10:11], v[4:5], v[62:63], v[10:11] op_sel_hi:[0,1,1]
	v_pk_fma_f32 v[10:11], v[4:5], v[64:65], v[10:11] op_sel:[1,0,0] op_sel_hi:[1,1,1]
	v_pk_mul_f32 v[18:19], v[74:75], v[26:27] op_sel_hi:[1,0]
	v_pk_mul_f32 v[20:21], v[76:77], v[26:27] op_sel_hi:[1,0]
	v_add_f32_dpp v10, v10, v10 quad_perm:[1,0,3,2] row_mask:0xf bank_mask:0xf bound_ctrl:1
	v_add_f32_dpp v11, v11, v11 quad_perm:[1,0,3,2] row_mask:0xf bank_mask:0xf bound_ctrl:1
	v_pk_fma_f32 v[18:19], v[2:3], v[66:67], v[18:19]
	v_add_f32_dpp v10, v10, v10 quad_perm:[2,3,0,1] row_mask:0xf bank_mask:0xf bound_ctrl:1
	v_add_f32_dpp v11, v11, v11 quad_perm:[2,3,0,1] row_mask:0xf bank_mask:0xf bound_ctrl:1
	v_pk_fma_f32 v[20:21], v[4:5], v[68:69], v[20:21]
	v_add_f32_dpp v10, v10, v10 row_half_mirror row_mask:0xf bank_mask:0xf bound_ctrl:1
	v_add_f32_dpp v11, v11, v11 row_half_mirror row_mask:0xf bank_mask:0xf bound_ctrl:1
	s_nop 0
	v_add_f32_dpp v10, v10, v10 row_mirror row_mask:0xf bank_mask:0xf bound_ctrl:1
	v_add_f32_dpp v11, v11, v11 row_mirror row_mask:0xf bank_mask:0xf bound_ctrl:1
	v_pk_fma_f32 v[2:3], v[70:71], v[10:11], v[18:19] op_sel_hi:[1,0,1]
	v_pk_fma_f32 v[4:5], v[72:73], v[10:11], v[20:21] op_sel_hi:[1,0,1]
	v_mov_b32_dpp v26, v24 row_newbcast:13 row_mask:0xf bank_mask:0xf
	v_fmac_f32_e32 v11, v120, v10
	ds_read_b128 v[186:189], v6 offset:19200
	ds_read_b128 v[190:193], v6 offset:19216
	ds_read_b128 v[194:197], v6 offset:19232
	ds_read_b128 v[198:201], v6 offset:19248
	ds_read_b128 v[202:205], v6 offset:19264
	s_waitcnt lgkmcnt(12)
	v_pk_mul_f32 v[12:13], v[2:3], v[78:79] op_sel_hi:[0,1]
	v_pk_fma_f32 v[12:13], v[2:3], v[80:81], v[12:13] op_sel:[1,0,0] op_sel_hi:[1,1,1]
	v_pk_fma_f32 v[12:13], v[4:5], v[82:83], v[12:13] op_sel_hi:[0,1,1]
	v_pk_fma_f32 v[12:13], v[4:5], v[84:85], v[12:13] op_sel:[1,0,0] op_sel_hi:[1,1,1]
	v_pk_mul_f32 v[18:19], v[94:95], v[26:27] op_sel_hi:[1,0]
	v_pk_mul_f32 v[20:21], v[96:97], v[26:27] op_sel_hi:[1,0]
	v_add_f32_dpp v12, v12, v12 quad_perm:[1,0,3,2] row_mask:0xf bank_mask:0xf bound_ctrl:1
	v_add_f32_dpp v13, v13, v13 quad_perm:[1,0,3,2] row_mask:0xf bank_mask:0xf bound_ctrl:1
	v_pk_fma_f32 v[18:19], v[2:3], v[86:87], v[18:19]
	v_add_f32_dpp v12, v12, v12 quad_perm:[2,3,0,1] row_mask:0xf bank_mask:0xf bound_ctrl:1
	v_add_f32_dpp v13, v13, v13 quad_perm:[2,3,0,1] row_mask:0xf bank_mask:0xf bound_ctrl:1
	v_pk_fma_f32 v[20:21], v[4:5], v[88:89], v[20:21]
	v_add_f32_dpp v12, v12, v12 row_half_mirror row_mask:0xf bank_mask:0xf bound_ctrl:1
	v_add_f32_dpp v13, v13, v13 row_half_mirror row_mask:0xf bank_mask:0xf bound_ctrl:1
	s_nop 0
	v_add_f32_dpp v12, v12, v12 row_mirror row_mask:0xf bank_mask:0xf bound_ctrl:1
	v_add_f32_dpp v13, v13, v13 row_mirror row_mask:0xf bank_mask:0xf bound_ctrl:1
	v_pk_fma_f32 v[2:3], v[90:91], v[12:13], v[18:19] op_sel_hi:[1,0,1]
	v_pk_fma_f32 v[4:5], v[92:93], v[12:13], v[20:21] op_sel_hi:[1,0,1]
	v_mov_b32_dpp v26, v24 row_newbcast:14 row_mask:0xf bank_mask:0xf
	v_fmac_f32_e32 v13, v121, v12
	ds_write2_b32 v9, v11, v13 offset0:192 offset1:208
	ds_read_b128 v[58:61], v6 offset:20480
	ds_read_b128 v[62:65], v6 offset:20496
	ds_read_b128 v[66:69], v6 offset:20512
	ds_read_b128 v[70:73], v6 offset:20528
	ds_read_b128 v[74:77], v6 offset:20544
	ds_read_b64 v[120:121], v8 offset:64
	s_waitcnt lgkmcnt(12)
	v_pk_mul_f32 v[14:15], v[2:3], v[98:99] op_sel_hi:[0,1]
	v_pk_fma_f32 v[14:15], v[2:3], v[100:101], v[14:15] op_sel:[1,0,0] op_sel_hi:[1,1,1]
	v_pk_fma_f32 v[14:15], v[4:5], v[102:103], v[14:15] op_sel_hi:[0,1,1]
	v_pk_fma_f32 v[14:15], v[4:5], v[104:105], v[14:15] op_sel:[1,0,0] op_sel_hi:[1,1,1]
	v_pk_mul_f32 v[18:19], v[114:115], v[26:27] op_sel_hi:[1,0]
	v_pk_mul_f32 v[20:21], v[116:117], v[26:27] op_sel_hi:[1,0]
	v_add_f32_dpp v14, v14, v14 quad_perm:[1,0,3,2] row_mask:0xf bank_mask:0xf bound_ctrl:1
	v_add_f32_dpp v15, v15, v15 quad_perm:[1,0,3,2] row_mask:0xf bank_mask:0xf bound_ctrl:1
	v_pk_fma_f32 v[18:19], v[2:3], v[106:107], v[18:19]
	v_add_f32_dpp v14, v14, v14 quad_perm:[2,3,0,1] row_mask:0xf bank_mask:0xf bound_ctrl:1
	v_add_f32_dpp v15, v15, v15 quad_perm:[2,3,0,1] row_mask:0xf bank_mask:0xf bound_ctrl:1
	v_pk_fma_f32 v[20:21], v[4:5], v[108:109], v[20:21]
	v_add_f32_dpp v14, v14, v14 row_half_mirror row_mask:0xf bank_mask:0xf bound_ctrl:1
	v_add_f32_dpp v15, v15, v15 row_half_mirror row_mask:0xf bank_mask:0xf bound_ctrl:1
	s_nop 0
	v_add_f32_dpp v14, v14, v14 row_mirror row_mask:0xf bank_mask:0xf bound_ctrl:1
	v_add_f32_dpp v15, v15, v15 row_mirror row_mask:0xf bank_mask:0xf bound_ctrl:1
	v_pk_fma_f32 v[2:3], v[110:111], v[14:15], v[18:19] op_sel_hi:[1,0,1]
	v_pk_fma_f32 v[4:5], v[112:113], v[14:15], v[20:21] op_sel_hi:[1,0,1]
	v_mov_b32_dpp v26, v24 row_newbcast:15 row_mask:0xf bank_mask:0xf
	v_fmac_f32_e32 v15, v208, v14
	ds_read_b128 v[78:81], v6 offset:21760
	ds_read_b128 v[82:85], v6 offset:21776
	ds_read_b128 v[86:89], v6 offset:21792
	ds_read_b128 v[90:93], v6 offset:21808
	ds_read_b128 v[94:97], v6 offset:21824
	s_waitcnt lgkmcnt(12)
	v_pk_mul_f32 v[16:17], v[2:3], v[186:187] op_sel_hi:[0,1]
	v_pk_fma_f32 v[16:17], v[2:3], v[188:189], v[16:17] op_sel:[1,0,0] op_sel_hi:[1,1,1]
	v_pk_fma_f32 v[16:17], v[4:5], v[190:191], v[16:17] op_sel_hi:[0,1,1]
	v_pk_fma_f32 v[16:17], v[4:5], v[192:193], v[16:17] op_sel:[1,0,0] op_sel_hi:[1,1,1]
	v_pk_mul_f32 v[18:19], v[202:203], v[26:27] op_sel_hi:[1,0]
	v_pk_mul_f32 v[20:21], v[204:205], v[26:27] op_sel_hi:[1,0]
	v_add_f32_dpp v16, v16, v16 quad_perm:[1,0,3,2] row_mask:0xf bank_mask:0xf bound_ctrl:1
	v_add_f32_dpp v17, v17, v17 quad_perm:[1,0,3,2] row_mask:0xf bank_mask:0xf bound_ctrl:1
	v_pk_fma_f32 v[18:19], v[2:3], v[194:195], v[18:19]
	v_add_f32_dpp v16, v16, v16 quad_perm:[2,3,0,1] row_mask:0xf bank_mask:0xf bound_ctrl:1
	v_add_f32_dpp v17, v17, v17 quad_perm:[2,3,0,1] row_mask:0xf bank_mask:0xf bound_ctrl:1
	v_pk_fma_f32 v[20:21], v[4:5], v[196:197], v[20:21]
	v_add_f32_dpp v16, v16, v16 row_half_mirror row_mask:0xf bank_mask:0xf bound_ctrl:1
	v_add_f32_dpp v17, v17, v17 row_half_mirror row_mask:0xf bank_mask:0xf bound_ctrl:1
	s_nop 0
	v_add_f32_dpp v16, v16, v16 row_mirror row_mask:0xf bank_mask:0xf bound_ctrl:1
	v_add_f32_dpp v17, v17, v17 row_mirror row_mask:0xf bank_mask:0xf bound_ctrl:1
	v_pk_fma_f32 v[2:3], v[198:199], v[16:17], v[18:19] op_sel_hi:[1,0,1]
	v_pk_fma_f32 v[4:5], v[200:201], v[16:17], v[20:21] op_sel_hi:[1,0,1]
	v_mov_b32_dpp v26, v25 row_newbcast:0 row_mask:0xf bank_mask:0xf
	v_fmac_f32_e32 v17, v209, v16
	ds_write2_b32 v9, v15, v17 offset0:224 offset1:240
	ds_read_b128 v[98:101], v6 offset:23040
	ds_read_b128 v[102:105], v6 offset:23056
	ds_read_b128 v[106:109], v6 offset:23072
	ds_read_b128 v[110:113], v6 offset:23088
	ds_read_b128 v[114:117], v6 offset:23104
	ds_read_b64 v[208:209], v8 offset:72
	s_waitcnt lgkmcnt(12)
	v_pk_mul_f32 v[10:11], v[2:3], v[58:59] op_sel_hi:[0,1]
	v_pk_fma_f32 v[10:11], v[2:3], v[60:61], v[10:11] op_sel:[1,0,0] op_sel_hi:[1,1,1]
	v_pk_fma_f32 v[10:11], v[4:5], v[62:63], v[10:11] op_sel_hi:[0,1,1]
	v_pk_fma_f32 v[10:11], v[4:5], v[64:65], v[10:11] op_sel:[1,0,0] op_sel_hi:[1,1,1]
	v_pk_mul_f32 v[18:19], v[74:75], v[26:27] op_sel_hi:[1,0]
	v_pk_mul_f32 v[20:21], v[76:77], v[26:27] op_sel_hi:[1,0]
	v_add_f32_dpp v10, v10, v10 quad_perm:[1,0,3,2] row_mask:0xf bank_mask:0xf bound_ctrl:1
	v_add_f32_dpp v11, v11, v11 quad_perm:[1,0,3,2] row_mask:0xf bank_mask:0xf bound_ctrl:1
	v_pk_fma_f32 v[18:19], v[2:3], v[66:67], v[18:19]
	v_add_f32_dpp v10, v10, v10 quad_perm:[2,3,0,1] row_mask:0xf bank_mask:0xf bound_ctrl:1
	v_add_f32_dpp v11, v11, v11 quad_perm:[2,3,0,1] row_mask:0xf bank_mask:0xf bound_ctrl:1
	v_pk_fma_f32 v[20:21], v[4:5], v[68:69], v[20:21]
	v_add_f32_dpp v10, v10, v10 row_half_mirror row_mask:0xf bank_mask:0xf bound_ctrl:1
	v_add_f32_dpp v11, v11, v11 row_half_mirror row_mask:0xf bank_mask:0xf bound_ctrl:1
	s_nop 0
	v_add_f32_dpp v10, v10, v10 row_mirror row_mask:0xf bank_mask:0xf bound_ctrl:1
	v_add_f32_dpp v11, v11, v11 row_mirror row_mask:0xf bank_mask:0xf bound_ctrl:1
	v_pk_fma_f32 v[2:3], v[70:71], v[10:11], v[18:19] op_sel_hi:[1,0,1]
	v_pk_fma_f32 v[4:5], v[72:73], v[10:11], v[20:21] op_sel_hi:[1,0,1]
	v_mov_b32_dpp v26, v25 row_newbcast:1 row_mask:0xf bank_mask:0xf
	v_fmac_f32_e32 v11, v120, v10
	ds_read_b128 v[186:189], v6 offset:24320
	ds_read_b128 v[190:193], v6 offset:24336
	ds_read_b128 v[194:197], v6 offset:24352
	ds_read_b128 v[198:201], v6 offset:24368
	ds_read_b128 v[202:205], v6 offset:24384
	s_waitcnt lgkmcnt(12)
	v_pk_mul_f32 v[12:13], v[2:3], v[78:79] op_sel_hi:[0,1]
	v_pk_fma_f32 v[12:13], v[2:3], v[80:81], v[12:13] op_sel:[1,0,0] op_sel_hi:[1,1,1]
	v_pk_fma_f32 v[12:13], v[4:5], v[82:83], v[12:13] op_sel_hi:[0,1,1]
	v_pk_fma_f32 v[12:13], v[4:5], v[84:85], v[12:13] op_sel:[1,0,0] op_sel_hi:[1,1,1]
	v_pk_mul_f32 v[18:19], v[94:95], v[26:27] op_sel_hi:[1,0]
	v_pk_mul_f32 v[20:21], v[96:97], v[26:27] op_sel_hi:[1,0]
	v_add_f32_dpp v12, v12, v12 quad_perm:[1,0,3,2] row_mask:0xf bank_mask:0xf bound_ctrl:1
	v_add_f32_dpp v13, v13, v13 quad_perm:[1,0,3,2] row_mask:0xf bank_mask:0xf bound_ctrl:1
	v_pk_fma_f32 v[18:19], v[2:3], v[86:87], v[18:19]
	v_add_f32_dpp v12, v12, v12 quad_perm:[2,3,0,1] row_mask:0xf bank_mask:0xf bound_ctrl:1
	v_add_f32_dpp v13, v13, v13 quad_perm:[2,3,0,1] row_mask:0xf bank_mask:0xf bound_ctrl:1
	v_pk_fma_f32 v[20:21], v[4:5], v[88:89], v[20:21]
	v_add_f32_dpp v12, v12, v12 row_half_mirror row_mask:0xf bank_mask:0xf bound_ctrl:1
	v_add_f32_dpp v13, v13, v13 row_half_mirror row_mask:0xf bank_mask:0xf bound_ctrl:1
	s_nop 0
	v_add_f32_dpp v12, v12, v12 row_mirror row_mask:0xf bank_mask:0xf bound_ctrl:1
	v_add_f32_dpp v13, v13, v13 row_mirror row_mask:0xf bank_mask:0xf bound_ctrl:1
	v_pk_fma_f32 v[2:3], v[90:91], v[12:13], v[18:19] op_sel_hi:[1,0,1]
	v_pk_fma_f32 v[4:5], v[92:93], v[12:13], v[20:21] op_sel_hi:[1,0,1]
	v_mov_b32_dpp v26, v25 row_newbcast:2 row_mask:0xf bank_mask:0xf
	v_fmac_f32_e32 v13, v121, v12
	ds_write2_b32 v22, v11, v13 offset1:16
	ds_read_b128 v[58:61], v6 offset:25600
	ds_read_b128 v[62:65], v6 offset:25616
	ds_read_b128 v[66:69], v6 offset:25632
	ds_read_b128 v[70:73], v6 offset:25648
	ds_read_b128 v[74:77], v6 offset:25664
	ds_read_b64 v[120:121], v8 offset:80
	s_waitcnt lgkmcnt(12)
	v_pk_mul_f32 v[14:15], v[2:3], v[98:99] op_sel_hi:[0,1]
	v_pk_fma_f32 v[14:15], v[2:3], v[100:101], v[14:15] op_sel:[1,0,0] op_sel_hi:[1,1,1]
	v_pk_fma_f32 v[14:15], v[4:5], v[102:103], v[14:15] op_sel_hi:[0,1,1]
	v_pk_fma_f32 v[14:15], v[4:5], v[104:105], v[14:15] op_sel:[1,0,0] op_sel_hi:[1,1,1]
	v_pk_mul_f32 v[18:19], v[114:115], v[26:27] op_sel_hi:[1,0]
	v_pk_mul_f32 v[20:21], v[116:117], v[26:27] op_sel_hi:[1,0]
	v_add_f32_dpp v14, v14, v14 quad_perm:[1,0,3,2] row_mask:0xf bank_mask:0xf bound_ctrl:1
	v_add_f32_dpp v15, v15, v15 quad_perm:[1,0,3,2] row_mask:0xf bank_mask:0xf bound_ctrl:1
	v_pk_fma_f32 v[18:19], v[2:3], v[106:107], v[18:19]
	v_add_f32_dpp v14, v14, v14 quad_perm:[2,3,0,1] row_mask:0xf bank_mask:0xf bound_ctrl:1
	v_add_f32_dpp v15, v15, v15 quad_perm:[2,3,0,1] row_mask:0xf bank_mask:0xf bound_ctrl:1
	v_pk_fma_f32 v[20:21], v[4:5], v[108:109], v[20:21]
	v_add_f32_dpp v14, v14, v14 row_half_mirror row_mask:0xf bank_mask:0xf bound_ctrl:1
	v_add_f32_dpp v15, v15, v15 row_half_mirror row_mask:0xf bank_mask:0xf bound_ctrl:1
	s_nop 0
	v_add_f32_dpp v14, v14, v14 row_mirror row_mask:0xf bank_mask:0xf bound_ctrl:1
	v_add_f32_dpp v15, v15, v15 row_mirror row_mask:0xf bank_mask:0xf bound_ctrl:1
	v_pk_fma_f32 v[2:3], v[110:111], v[14:15], v[18:19] op_sel_hi:[1,0,1]
	v_pk_fma_f32 v[4:5], v[112:113], v[14:15], v[20:21] op_sel_hi:[1,0,1]
	v_mov_b32_dpp v26, v25 row_newbcast:3 row_mask:0xf bank_mask:0xf
	v_fmac_f32_e32 v15, v208, v14
	ds_read_b128 v[78:81], v6 offset:26880
	ds_read_b128 v[82:85], v6 offset:26896
	ds_read_b128 v[86:89], v6 offset:26912
	ds_read_b128 v[90:93], v6 offset:26928
	ds_read_b128 v[94:97], v6 offset:26944
	s_waitcnt lgkmcnt(12)
	v_pk_mul_f32 v[16:17], v[2:3], v[186:187] op_sel_hi:[0,1]
	v_pk_fma_f32 v[16:17], v[2:3], v[188:189], v[16:17] op_sel:[1,0,0] op_sel_hi:[1,1,1]
	v_pk_fma_f32 v[16:17], v[4:5], v[190:191], v[16:17] op_sel_hi:[0,1,1]
	v_pk_fma_f32 v[16:17], v[4:5], v[192:193], v[16:17] op_sel:[1,0,0] op_sel_hi:[1,1,1]
	v_pk_mul_f32 v[18:19], v[202:203], v[26:27] op_sel_hi:[1,0]
	v_pk_mul_f32 v[20:21], v[204:205], v[26:27] op_sel_hi:[1,0]
	v_add_f32_dpp v16, v16, v16 quad_perm:[1,0,3,2] row_mask:0xf bank_mask:0xf bound_ctrl:1
	v_add_f32_dpp v17, v17, v17 quad_perm:[1,0,3,2] row_mask:0xf bank_mask:0xf bound_ctrl:1
	v_pk_fma_f32 v[18:19], v[2:3], v[194:195], v[18:19]
	v_add_f32_dpp v16, v16, v16 quad_perm:[2,3,0,1] row_mask:0xf bank_mask:0xf bound_ctrl:1
	v_add_f32_dpp v17, v17, v17 quad_perm:[2,3,0,1] row_mask:0xf bank_mask:0xf bound_ctrl:1
	v_pk_fma_f32 v[20:21], v[4:5], v[196:197], v[20:21]
	v_add_f32_dpp v16, v16, v16 row_half_mirror row_mask:0xf bank_mask:0xf bound_ctrl:1
	v_add_f32_dpp v17, v17, v17 row_half_mirror row_mask:0xf bank_mask:0xf bound_ctrl:1
	s_nop 0
	v_add_f32_dpp v16, v16, v16 row_mirror row_mask:0xf bank_mask:0xf bound_ctrl:1
	v_add_f32_dpp v17, v17, v17 row_mirror row_mask:0xf bank_mask:0xf bound_ctrl:1
	v_pk_fma_f32 v[2:3], v[198:199], v[16:17], v[18:19] op_sel_hi:[1,0,1]
	v_pk_fma_f32 v[4:5], v[200:201], v[16:17], v[20:21] op_sel_hi:[1,0,1]
	v_mov_b32_dpp v26, v25 row_newbcast:4 row_mask:0xf bank_mask:0xf
	v_fmac_f32_e32 v17, v209, v16
	ds_write2_b32 v22, v15, v17 offset0:32 offset1:48
	ds_read_b128 v[98:101], v6 offset:28160
	ds_read_b128 v[102:105], v6 offset:28176
	ds_read_b128 v[106:109], v6 offset:28192
	ds_read_b128 v[110:113], v6 offset:28208
	ds_read_b128 v[114:117], v6 offset:28224
	ds_read_b64 v[208:209], v8 offset:88
	s_waitcnt lgkmcnt(12)
	v_pk_mul_f32 v[10:11], v[2:3], v[58:59] op_sel_hi:[0,1]
	v_pk_fma_f32 v[10:11], v[2:3], v[60:61], v[10:11] op_sel:[1,0,0] op_sel_hi:[1,1,1]
	v_pk_fma_f32 v[10:11], v[4:5], v[62:63], v[10:11] op_sel_hi:[0,1,1]
	v_pk_fma_f32 v[10:11], v[4:5], v[64:65], v[10:11] op_sel:[1,0,0] op_sel_hi:[1,1,1]
	v_pk_mul_f32 v[18:19], v[74:75], v[26:27] op_sel_hi:[1,0]
	v_pk_mul_f32 v[20:21], v[76:77], v[26:27] op_sel_hi:[1,0]
	v_add_f32_dpp v10, v10, v10 quad_perm:[1,0,3,2] row_mask:0xf bank_mask:0xf bound_ctrl:1
	v_add_f32_dpp v11, v11, v11 quad_perm:[1,0,3,2] row_mask:0xf bank_mask:0xf bound_ctrl:1
	v_pk_fma_f32 v[18:19], v[2:3], v[66:67], v[18:19]
	v_add_f32_dpp v10, v10, v10 quad_perm:[2,3,0,1] row_mask:0xf bank_mask:0xf bound_ctrl:1
	v_add_f32_dpp v11, v11, v11 quad_perm:[2,3,0,1] row_mask:0xf bank_mask:0xf bound_ctrl:1
	v_pk_fma_f32 v[20:21], v[4:5], v[68:69], v[20:21]
	v_add_f32_dpp v10, v10, v10 row_half_mirror row_mask:0xf bank_mask:0xf bound_ctrl:1
	v_add_f32_dpp v11, v11, v11 row_half_mirror row_mask:0xf bank_mask:0xf bound_ctrl:1
	s_nop 0
	v_add_f32_dpp v10, v10, v10 row_mirror row_mask:0xf bank_mask:0xf bound_ctrl:1
	v_add_f32_dpp v11, v11, v11 row_mirror row_mask:0xf bank_mask:0xf bound_ctrl:1
	v_pk_fma_f32 v[2:3], v[70:71], v[10:11], v[18:19] op_sel_hi:[1,0,1]
	v_pk_fma_f32 v[4:5], v[72:73], v[10:11], v[20:21] op_sel_hi:[1,0,1]
	v_mov_b32_dpp v26, v25 row_newbcast:5 row_mask:0xf bank_mask:0xf
	v_fmac_f32_e32 v11, v120, v10
	ds_read_b128 v[186:189], v6 offset:29440
	ds_read_b128 v[190:193], v6 offset:29456
	ds_read_b128 v[194:197], v6 offset:29472
	ds_read_b128 v[198:201], v6 offset:29488
	ds_read_b128 v[202:205], v6 offset:29504
	s_waitcnt lgkmcnt(12)
	v_pk_mul_f32 v[12:13], v[2:3], v[78:79] op_sel_hi:[0,1]
	v_pk_fma_f32 v[12:13], v[2:3], v[80:81], v[12:13] op_sel:[1,0,0] op_sel_hi:[1,1,1]
	v_pk_fma_f32 v[12:13], v[4:5], v[82:83], v[12:13] op_sel_hi:[0,1,1]
	v_pk_fma_f32 v[12:13], v[4:5], v[84:85], v[12:13] op_sel:[1,0,0] op_sel_hi:[1,1,1]
	v_pk_mul_f32 v[18:19], v[94:95], v[26:27] op_sel_hi:[1,0]
	v_pk_mul_f32 v[20:21], v[96:97], v[26:27] op_sel_hi:[1,0]
	v_add_f32_dpp v12, v12, v12 quad_perm:[1,0,3,2] row_mask:0xf bank_mask:0xf bound_ctrl:1
	v_add_f32_dpp v13, v13, v13 quad_perm:[1,0,3,2] row_mask:0xf bank_mask:0xf bound_ctrl:1
	v_pk_fma_f32 v[18:19], v[2:3], v[86:87], v[18:19]
	v_add_f32_dpp v12, v12, v12 quad_perm:[2,3,0,1] row_mask:0xf bank_mask:0xf bound_ctrl:1
	v_add_f32_dpp v13, v13, v13 quad_perm:[2,3,0,1] row_mask:0xf bank_mask:0xf bound_ctrl:1
	v_pk_fma_f32 v[20:21], v[4:5], v[88:89], v[20:21]
	v_add_f32_dpp v12, v12, v12 row_half_mirror row_mask:0xf bank_mask:0xf bound_ctrl:1
	v_add_f32_dpp v13, v13, v13 row_half_mirror row_mask:0xf bank_mask:0xf bound_ctrl:1
	s_nop 0
	v_add_f32_dpp v12, v12, v12 row_mirror row_mask:0xf bank_mask:0xf bound_ctrl:1
	v_add_f32_dpp v13, v13, v13 row_mirror row_mask:0xf bank_mask:0xf bound_ctrl:1
	v_pk_fma_f32 v[2:3], v[90:91], v[12:13], v[18:19] op_sel_hi:[1,0,1]
	v_pk_fma_f32 v[4:5], v[92:93], v[12:13], v[20:21] op_sel_hi:[1,0,1]
	v_mov_b32_dpp v26, v25 row_newbcast:6 row_mask:0xf bank_mask:0xf
	v_fmac_f32_e32 v13, v121, v12
	ds_write2_b32 v22, v11, v13 offset0:64 offset1:80
	ds_read_b128 v[58:61], v6 offset:30720
	ds_read_b128 v[62:65], v6 offset:30736
	ds_read_b128 v[66:69], v6 offset:30752
	ds_read_b128 v[70:73], v6 offset:30768
	ds_read_b128 v[74:77], v6 offset:30784
	ds_read_b64 v[120:121], v8 offset:96
	s_waitcnt lgkmcnt(12)
	v_pk_mul_f32 v[14:15], v[2:3], v[98:99] op_sel_hi:[0,1]
	v_pk_fma_f32 v[14:15], v[2:3], v[100:101], v[14:15] op_sel:[1,0,0] op_sel_hi:[1,1,1]
	v_pk_fma_f32 v[14:15], v[4:5], v[102:103], v[14:15] op_sel_hi:[0,1,1]
	v_pk_fma_f32 v[14:15], v[4:5], v[104:105], v[14:15] op_sel:[1,0,0] op_sel_hi:[1,1,1]
	v_pk_mul_f32 v[18:19], v[114:115], v[26:27] op_sel_hi:[1,0]
	v_pk_mul_f32 v[20:21], v[116:117], v[26:27] op_sel_hi:[1,0]
	v_add_f32_dpp v14, v14, v14 quad_perm:[1,0,3,2] row_mask:0xf bank_mask:0xf bound_ctrl:1
	v_add_f32_dpp v15, v15, v15 quad_perm:[1,0,3,2] row_mask:0xf bank_mask:0xf bound_ctrl:1
	v_pk_fma_f32 v[18:19], v[2:3], v[106:107], v[18:19]
	v_add_f32_dpp v14, v14, v14 quad_perm:[2,3,0,1] row_mask:0xf bank_mask:0xf bound_ctrl:1
	v_add_f32_dpp v15, v15, v15 quad_perm:[2,3,0,1] row_mask:0xf bank_mask:0xf bound_ctrl:1
	v_pk_fma_f32 v[20:21], v[4:5], v[108:109], v[20:21]
	v_add_f32_dpp v14, v14, v14 row_half_mirror row_mask:0xf bank_mask:0xf bound_ctrl:1
	v_add_f32_dpp v15, v15, v15 row_half_mirror row_mask:0xf bank_mask:0xf bound_ctrl:1
	s_nop 0
	v_add_f32_dpp v14, v14, v14 row_mirror row_mask:0xf bank_mask:0xf bound_ctrl:1
	v_add_f32_dpp v15, v15, v15 row_mirror row_mask:0xf bank_mask:0xf bound_ctrl:1
	v_pk_fma_f32 v[2:3], v[110:111], v[14:15], v[18:19] op_sel_hi:[1,0,1]
	v_pk_fma_f32 v[4:5], v[112:113], v[14:15], v[20:21] op_sel_hi:[1,0,1]
	v_mov_b32_dpp v26, v25 row_newbcast:7 row_mask:0xf bank_mask:0xf
	v_fmac_f32_e32 v15, v208, v14
	ds_read_b128 v[78:81], v6 offset:32000
	ds_read_b128 v[82:85], v6 offset:32016
	ds_read_b128 v[86:89], v6 offset:32032
	ds_read_b128 v[90:93], v6 offset:32048
	ds_read_b128 v[94:97], v6 offset:32064
	s_waitcnt lgkmcnt(12)
	v_pk_mul_f32 v[16:17], v[2:3], v[186:187] op_sel_hi:[0,1]
	v_pk_fma_f32 v[16:17], v[2:3], v[188:189], v[16:17] op_sel:[1,0,0] op_sel_hi:[1,1,1]
	v_pk_fma_f32 v[16:17], v[4:5], v[190:191], v[16:17] op_sel_hi:[0,1,1]
	v_pk_fma_f32 v[16:17], v[4:5], v[192:193], v[16:17] op_sel:[1,0,0] op_sel_hi:[1,1,1]
	v_pk_mul_f32 v[18:19], v[202:203], v[26:27] op_sel_hi:[1,0]
	v_pk_mul_f32 v[20:21], v[204:205], v[26:27] op_sel_hi:[1,0]
	v_add_f32_dpp v16, v16, v16 quad_perm:[1,0,3,2] row_mask:0xf bank_mask:0xf bound_ctrl:1
	v_add_f32_dpp v17, v17, v17 quad_perm:[1,0,3,2] row_mask:0xf bank_mask:0xf bound_ctrl:1
	v_pk_fma_f32 v[18:19], v[2:3], v[194:195], v[18:19]
	v_add_f32_dpp v16, v16, v16 quad_perm:[2,3,0,1] row_mask:0xf bank_mask:0xf bound_ctrl:1
	v_add_f32_dpp v17, v17, v17 quad_perm:[2,3,0,1] row_mask:0xf bank_mask:0xf bound_ctrl:1
	v_pk_fma_f32 v[20:21], v[4:5], v[196:197], v[20:21]
	v_add_f32_dpp v16, v16, v16 row_half_mirror row_mask:0xf bank_mask:0xf bound_ctrl:1
	v_add_f32_dpp v17, v17, v17 row_half_mirror row_mask:0xf bank_mask:0xf bound_ctrl:1
	s_nop 0
	v_add_f32_dpp v16, v16, v16 row_mirror row_mask:0xf bank_mask:0xf bound_ctrl:1
	v_add_f32_dpp v17, v17, v17 row_mirror row_mask:0xf bank_mask:0xf bound_ctrl:1
	v_pk_fma_f32 v[2:3], v[198:199], v[16:17], v[18:19] op_sel_hi:[1,0,1]
	v_pk_fma_f32 v[4:5], v[200:201], v[16:17], v[20:21] op_sel_hi:[1,0,1]
	v_mov_b32_dpp v26, v25 row_newbcast:8 row_mask:0xf bank_mask:0xf
	v_fmac_f32_e32 v17, v209, v16
	ds_write2_b32 v22, v15, v17 offset0:96 offset1:112
	ds_read_b128 v[98:101], v6 offset:33280
	ds_read_b128 v[102:105], v6 offset:33296
	ds_read_b128 v[106:109], v6 offset:33312
	ds_read_b128 v[110:113], v6 offset:33328
	ds_read_b128 v[114:117], v6 offset:33344
	ds_read_b64 v[208:209], v8 offset:104
	s_waitcnt lgkmcnt(12)
	v_pk_mul_f32 v[10:11], v[2:3], v[58:59] op_sel_hi:[0,1]
	v_pk_fma_f32 v[10:11], v[2:3], v[60:61], v[10:11] op_sel:[1,0,0] op_sel_hi:[1,1,1]
	v_pk_fma_f32 v[10:11], v[4:5], v[62:63], v[10:11] op_sel_hi:[0,1,1]
	v_pk_fma_f32 v[10:11], v[4:5], v[64:65], v[10:11] op_sel:[1,0,0] op_sel_hi:[1,1,1]
	v_pk_mul_f32 v[18:19], v[74:75], v[26:27] op_sel_hi:[1,0]
	v_pk_mul_f32 v[20:21], v[76:77], v[26:27] op_sel_hi:[1,0]
	v_add_f32_dpp v10, v10, v10 quad_perm:[1,0,3,2] row_mask:0xf bank_mask:0xf bound_ctrl:1
	v_add_f32_dpp v11, v11, v11 quad_perm:[1,0,3,2] row_mask:0xf bank_mask:0xf bound_ctrl:1
	v_pk_fma_f32 v[18:19], v[2:3], v[66:67], v[18:19]
	v_add_f32_dpp v10, v10, v10 quad_perm:[2,3,0,1] row_mask:0xf bank_mask:0xf bound_ctrl:1
	v_add_f32_dpp v11, v11, v11 quad_perm:[2,3,0,1] row_mask:0xf bank_mask:0xf bound_ctrl:1
	v_pk_fma_f32 v[20:21], v[4:5], v[68:69], v[20:21]
	v_add_f32_dpp v10, v10, v10 row_half_mirror row_mask:0xf bank_mask:0xf bound_ctrl:1
	v_add_f32_dpp v11, v11, v11 row_half_mirror row_mask:0xf bank_mask:0xf bound_ctrl:1
	s_nop 0
	v_add_f32_dpp v10, v10, v10 row_mirror row_mask:0xf bank_mask:0xf bound_ctrl:1
	v_add_f32_dpp v11, v11, v11 row_mirror row_mask:0xf bank_mask:0xf bound_ctrl:1
	v_pk_fma_f32 v[2:3], v[70:71], v[10:11], v[18:19] op_sel_hi:[1,0,1]
	v_pk_fma_f32 v[4:5], v[72:73], v[10:11], v[20:21] op_sel_hi:[1,0,1]
	v_mov_b32_dpp v26, v25 row_newbcast:9 row_mask:0xf bank_mask:0xf
	v_fmac_f32_e32 v11, v120, v10
	ds_read_b128 v[186:189], v6 offset:34560
	ds_read_b128 v[190:193], v6 offset:34576
	ds_read_b128 v[194:197], v6 offset:34592
	ds_read_b128 v[198:201], v6 offset:34608
	ds_read_b128 v[202:205], v6 offset:34624
	s_waitcnt lgkmcnt(12)
	v_pk_mul_f32 v[12:13], v[2:3], v[78:79] op_sel_hi:[0,1]
	v_pk_fma_f32 v[12:13], v[2:3], v[80:81], v[12:13] op_sel:[1,0,0] op_sel_hi:[1,1,1]
	v_pk_fma_f32 v[12:13], v[4:5], v[82:83], v[12:13] op_sel_hi:[0,1,1]
	v_pk_fma_f32 v[12:13], v[4:5], v[84:85], v[12:13] op_sel:[1,0,0] op_sel_hi:[1,1,1]
	v_pk_mul_f32 v[18:19], v[94:95], v[26:27] op_sel_hi:[1,0]
	v_pk_mul_f32 v[20:21], v[96:97], v[26:27] op_sel_hi:[1,0]
	v_add_f32_dpp v12, v12, v12 quad_perm:[1,0,3,2] row_mask:0xf bank_mask:0xf bound_ctrl:1
	v_add_f32_dpp v13, v13, v13 quad_perm:[1,0,3,2] row_mask:0xf bank_mask:0xf bound_ctrl:1
	v_pk_fma_f32 v[18:19], v[2:3], v[86:87], v[18:19]
	v_add_f32_dpp v12, v12, v12 quad_perm:[2,3,0,1] row_mask:0xf bank_mask:0xf bound_ctrl:1
	v_add_f32_dpp v13, v13, v13 quad_perm:[2,3,0,1] row_mask:0xf bank_mask:0xf bound_ctrl:1
	v_pk_fma_f32 v[20:21], v[4:5], v[88:89], v[20:21]
	v_add_f32_dpp v12, v12, v12 row_half_mirror row_mask:0xf bank_mask:0xf bound_ctrl:1
	v_add_f32_dpp v13, v13, v13 row_half_mirror row_mask:0xf bank_mask:0xf bound_ctrl:1
	s_nop 0
	v_add_f32_dpp v12, v12, v12 row_mirror row_mask:0xf bank_mask:0xf bound_ctrl:1
	v_add_f32_dpp v13, v13, v13 row_mirror row_mask:0xf bank_mask:0xf bound_ctrl:1
	v_pk_fma_f32 v[2:3], v[90:91], v[12:13], v[18:19] op_sel_hi:[1,0,1]
	v_pk_fma_f32 v[4:5], v[92:93], v[12:13], v[20:21] op_sel_hi:[1,0,1]
	v_mov_b32_dpp v26, v25 row_newbcast:10 row_mask:0xf bank_mask:0xf
	v_fmac_f32_e32 v13, v121, v12
	ds_write2_b32 v22, v11, v13 offset0:128 offset1:144
	ds_read_b128 v[58:61], v6 offset:35840
	ds_read_b128 v[62:65], v6 offset:35856
	ds_read_b128 v[66:69], v6 offset:35872
	ds_read_b128 v[70:73], v6 offset:35888
	ds_read_b128 v[74:77], v6 offset:35904
	ds_read_b64 v[120:121], v8 offset:112
	s_waitcnt lgkmcnt(12)
	v_pk_mul_f32 v[14:15], v[2:3], v[98:99] op_sel_hi:[0,1]
	v_pk_fma_f32 v[14:15], v[2:3], v[100:101], v[14:15] op_sel:[1,0,0] op_sel_hi:[1,1,1]
	v_pk_fma_f32 v[14:15], v[4:5], v[102:103], v[14:15] op_sel_hi:[0,1,1]
	v_pk_fma_f32 v[14:15], v[4:5], v[104:105], v[14:15] op_sel:[1,0,0] op_sel_hi:[1,1,1]
	v_pk_mul_f32 v[18:19], v[114:115], v[26:27] op_sel_hi:[1,0]
	v_pk_mul_f32 v[20:21], v[116:117], v[26:27] op_sel_hi:[1,0]
	v_add_f32_dpp v14, v14, v14 quad_perm:[1,0,3,2] row_mask:0xf bank_mask:0xf bound_ctrl:1
	v_add_f32_dpp v15, v15, v15 quad_perm:[1,0,3,2] row_mask:0xf bank_mask:0xf bound_ctrl:1
	v_pk_fma_f32 v[18:19], v[2:3], v[106:107], v[18:19]
	v_add_f32_dpp v14, v14, v14 quad_perm:[2,3,0,1] row_mask:0xf bank_mask:0xf bound_ctrl:1
	v_add_f32_dpp v15, v15, v15 quad_perm:[2,3,0,1] row_mask:0xf bank_mask:0xf bound_ctrl:1
	v_pk_fma_f32 v[20:21], v[4:5], v[108:109], v[20:21]
	v_add_f32_dpp v14, v14, v14 row_half_mirror row_mask:0xf bank_mask:0xf bound_ctrl:1
	v_add_f32_dpp v15, v15, v15 row_half_mirror row_mask:0xf bank_mask:0xf bound_ctrl:1
	s_nop 0
	v_add_f32_dpp v14, v14, v14 row_mirror row_mask:0xf bank_mask:0xf bound_ctrl:1
	v_add_f32_dpp v15, v15, v15 row_mirror row_mask:0xf bank_mask:0xf bound_ctrl:1
	v_pk_fma_f32 v[2:3], v[110:111], v[14:15], v[18:19] op_sel_hi:[1,0,1]
	v_pk_fma_f32 v[4:5], v[112:113], v[14:15], v[20:21] op_sel_hi:[1,0,1]
	v_mov_b32_dpp v26, v25 row_newbcast:11 row_mask:0xf bank_mask:0xf
	v_fmac_f32_e32 v15, v208, v14
	ds_read_b128 v[78:81], v6 offset:37120
	ds_read_b128 v[82:85], v6 offset:37136
	ds_read_b128 v[86:89], v6 offset:37152
	ds_read_b128 v[90:93], v6 offset:37168
	ds_read_b128 v[94:97], v6 offset:37184
	s_waitcnt lgkmcnt(12)
	v_pk_mul_f32 v[16:17], v[2:3], v[186:187] op_sel_hi:[0,1]
	v_pk_fma_f32 v[16:17], v[2:3], v[188:189], v[16:17] op_sel:[1,0,0] op_sel_hi:[1,1,1]
	v_pk_fma_f32 v[16:17], v[4:5], v[190:191], v[16:17] op_sel_hi:[0,1,1]
	v_pk_fma_f32 v[16:17], v[4:5], v[192:193], v[16:17] op_sel:[1,0,0] op_sel_hi:[1,1,1]
	v_pk_mul_f32 v[18:19], v[202:203], v[26:27] op_sel_hi:[1,0]
	v_pk_mul_f32 v[20:21], v[204:205], v[26:27] op_sel_hi:[1,0]
	v_add_f32_dpp v16, v16, v16 quad_perm:[1,0,3,2] row_mask:0xf bank_mask:0xf bound_ctrl:1
	v_add_f32_dpp v17, v17, v17 quad_perm:[1,0,3,2] row_mask:0xf bank_mask:0xf bound_ctrl:1
	v_pk_fma_f32 v[18:19], v[2:3], v[194:195], v[18:19]
	v_add_f32_dpp v16, v16, v16 quad_perm:[2,3,0,1] row_mask:0xf bank_mask:0xf bound_ctrl:1
	v_add_f32_dpp v17, v17, v17 quad_perm:[2,3,0,1] row_mask:0xf bank_mask:0xf bound_ctrl:1
	v_pk_fma_f32 v[20:21], v[4:5], v[196:197], v[20:21]
	v_add_f32_dpp v16, v16, v16 row_half_mirror row_mask:0xf bank_mask:0xf bound_ctrl:1
	v_add_f32_dpp v17, v17, v17 row_half_mirror row_mask:0xf bank_mask:0xf bound_ctrl:1
	s_nop 0
	v_add_f32_dpp v16, v16, v16 row_mirror row_mask:0xf bank_mask:0xf bound_ctrl:1
	v_add_f32_dpp v17, v17, v17 row_mirror row_mask:0xf bank_mask:0xf bound_ctrl:1
	v_pk_fma_f32 v[2:3], v[198:199], v[16:17], v[18:19] op_sel_hi:[1,0,1]
	v_pk_fma_f32 v[4:5], v[200:201], v[16:17], v[20:21] op_sel_hi:[1,0,1]
	v_mov_b32_dpp v26, v25 row_newbcast:12 row_mask:0xf bank_mask:0xf
	v_fmac_f32_e32 v17, v209, v16
	ds_write2_b32 v22, v15, v17 offset0:160 offset1:176
	ds_read_b128 v[98:101], v6 offset:38400
	ds_read_b128 v[102:105], v6 offset:38416
	ds_read_b128 v[106:109], v6 offset:38432
	ds_read_b128 v[110:113], v6 offset:38448
	ds_read_b128 v[114:117], v6 offset:38464
	ds_read_b64 v[208:209], v8 offset:120
	s_waitcnt lgkmcnt(12)
	v_pk_mul_f32 v[10:11], v[2:3], v[58:59] op_sel_hi:[0,1]
	v_pk_fma_f32 v[10:11], v[2:3], v[60:61], v[10:11] op_sel:[1,0,0] op_sel_hi:[1,1,1]
	v_pk_fma_f32 v[10:11], v[4:5], v[62:63], v[10:11] op_sel_hi:[0,1,1]
	v_pk_fma_f32 v[10:11], v[4:5], v[64:65], v[10:11] op_sel:[1,0,0] op_sel_hi:[1,1,1]
	v_pk_mul_f32 v[18:19], v[74:75], v[26:27] op_sel_hi:[1,0]
	v_pk_mul_f32 v[20:21], v[76:77], v[26:27] op_sel_hi:[1,0]
	v_add_f32_dpp v10, v10, v10 quad_perm:[1,0,3,2] row_mask:0xf bank_mask:0xf bound_ctrl:1
	v_add_f32_dpp v11, v11, v11 quad_perm:[1,0,3,2] row_mask:0xf bank_mask:0xf bound_ctrl:1
	v_pk_fma_f32 v[18:19], v[2:3], v[66:67], v[18:19]
	v_add_f32_dpp v10, v10, v10 quad_perm:[2,3,0,1] row_mask:0xf bank_mask:0xf bound_ctrl:1
	v_add_f32_dpp v11, v11, v11 quad_perm:[2,3,0,1] row_mask:0xf bank_mask:0xf bound_ctrl:1
	v_pk_fma_f32 v[20:21], v[4:5], v[68:69], v[20:21]
	v_add_f32_dpp v10, v10, v10 row_half_mirror row_mask:0xf bank_mask:0xf bound_ctrl:1
	v_add_f32_dpp v11, v11, v11 row_half_mirror row_mask:0xf bank_mask:0xf bound_ctrl:1
	s_nop 0
	v_add_f32_dpp v10, v10, v10 row_mirror row_mask:0xf bank_mask:0xf bound_ctrl:1
	v_add_f32_dpp v11, v11, v11 row_mirror row_mask:0xf bank_mask:0xf bound_ctrl:1
	v_pk_fma_f32 v[2:3], v[70:71], v[10:11], v[18:19] op_sel_hi:[1,0,1]
	v_pk_fma_f32 v[4:5], v[72:73], v[10:11], v[20:21] op_sel_hi:[1,0,1]
	v_mov_b32_dpp v26, v25 row_newbcast:13 row_mask:0xf bank_mask:0xf
	v_fmac_f32_e32 v11, v120, v10
	ds_read_b128 v[186:189], v6 offset:39680
	ds_read_b128 v[190:193], v6 offset:39696
	ds_read_b128 v[194:197], v6 offset:39712
	ds_read_b128 v[198:201], v6 offset:39728
	ds_read_b128 v[202:205], v6 offset:39744
	s_waitcnt lgkmcnt(12)
	v_pk_mul_f32 v[12:13], v[2:3], v[78:79] op_sel_hi:[0,1]
	v_pk_fma_f32 v[12:13], v[2:3], v[80:81], v[12:13] op_sel:[1,0,0] op_sel_hi:[1,1,1]
	v_pk_fma_f32 v[12:13], v[4:5], v[82:83], v[12:13] op_sel_hi:[0,1,1]
	v_pk_fma_f32 v[12:13], v[4:5], v[84:85], v[12:13] op_sel:[1,0,0] op_sel_hi:[1,1,1]
	v_pk_mul_f32 v[18:19], v[94:95], v[26:27] op_sel_hi:[1,0]
	v_pk_mul_f32 v[20:21], v[96:97], v[26:27] op_sel_hi:[1,0]
	v_add_f32_dpp v12, v12, v12 quad_perm:[1,0,3,2] row_mask:0xf bank_mask:0xf bound_ctrl:1
	v_add_f32_dpp v13, v13, v13 quad_perm:[1,0,3,2] row_mask:0xf bank_mask:0xf bound_ctrl:1
	v_pk_fma_f32 v[18:19], v[2:3], v[86:87], v[18:19]
	v_add_f32_dpp v12, v12, v12 quad_perm:[2,3,0,1] row_mask:0xf bank_mask:0xf bound_ctrl:1
	v_add_f32_dpp v13, v13, v13 quad_perm:[2,3,0,1] row_mask:0xf bank_mask:0xf bound_ctrl:1
	v_pk_fma_f32 v[20:21], v[4:5], v[88:89], v[20:21]
	v_add_f32_dpp v12, v12, v12 row_half_mirror row_mask:0xf bank_mask:0xf bound_ctrl:1
	v_add_f32_dpp v13, v13, v13 row_half_mirror row_mask:0xf bank_mask:0xf bound_ctrl:1
	s_nop 0
	v_add_f32_dpp v12, v12, v12 row_mirror row_mask:0xf bank_mask:0xf bound_ctrl:1
	v_add_f32_dpp v13, v13, v13 row_mirror row_mask:0xf bank_mask:0xf bound_ctrl:1
	v_pk_fma_f32 v[2:3], v[90:91], v[12:13], v[18:19] op_sel_hi:[1,0,1]
	v_pk_fma_f32 v[4:5], v[92:93], v[12:13], v[20:21] op_sel_hi:[1,0,1]
	v_mov_b32_dpp v26, v25 row_newbcast:14 row_mask:0xf bank_mask:0xf
	v_fmac_f32_e32 v13, v121, v12
	ds_write2_b32 v22, v11, v13 offset0:192 offset1:208
	s_waitcnt lgkmcnt(6)
	v_pk_mul_f32 v[14:15], v[2:3], v[98:99] op_sel_hi:[0,1]
	v_pk_fma_f32 v[14:15], v[2:3], v[100:101], v[14:15] op_sel:[1,0,0] op_sel_hi:[1,1,1]
	v_pk_fma_f32 v[14:15], v[4:5], v[102:103], v[14:15] op_sel_hi:[0,1,1]
	v_pk_fma_f32 v[14:15], v[4:5], v[104:105], v[14:15] op_sel:[1,0,0] op_sel_hi:[1,1,1]
	v_pk_mul_f32 v[18:19], v[114:115], v[26:27] op_sel_hi:[1,0]
	v_pk_mul_f32 v[20:21], v[116:117], v[26:27] op_sel_hi:[1,0]
	v_add_f32_dpp v14, v14, v14 quad_perm:[1,0,3,2] row_mask:0xf bank_mask:0xf bound_ctrl:1
	v_add_f32_dpp v15, v15, v15 quad_perm:[1,0,3,2] row_mask:0xf bank_mask:0xf bound_ctrl:1
	v_pk_fma_f32 v[18:19], v[2:3], v[106:107], v[18:19]
	v_add_f32_dpp v14, v14, v14 quad_perm:[2,3,0,1] row_mask:0xf bank_mask:0xf bound_ctrl:1
	v_add_f32_dpp v15, v15, v15 quad_perm:[2,3,0,1] row_mask:0xf bank_mask:0xf bound_ctrl:1
	v_pk_fma_f32 v[20:21], v[4:5], v[108:109], v[20:21]
	v_add_f32_dpp v14, v14, v14 row_half_mirror row_mask:0xf bank_mask:0xf bound_ctrl:1
	v_add_f32_dpp v15, v15, v15 row_half_mirror row_mask:0xf bank_mask:0xf bound_ctrl:1
	s_nop 0
	v_add_f32_dpp v14, v14, v14 row_mirror row_mask:0xf bank_mask:0xf bound_ctrl:1
	v_add_f32_dpp v15, v15, v15 row_mirror row_mask:0xf bank_mask:0xf bound_ctrl:1
	v_pk_fma_f32 v[2:3], v[110:111], v[14:15], v[18:19] op_sel_hi:[1,0,1]
	v_pk_fma_f32 v[4:5], v[112:113], v[14:15], v[20:21] op_sel_hi:[1,0,1]
	v_mov_b32_dpp v26, v25 row_newbcast:15 row_mask:0xf bank_mask:0xf
	v_fmac_f32_e32 v15, v208, v14
	s_waitcnt lgkmcnt(1)
	v_pk_mul_f32 v[16:17], v[2:3], v[186:187] op_sel_hi:[0,1]
	v_pk_fma_f32 v[16:17], v[2:3], v[188:189], v[16:17] op_sel:[1,0,0] op_sel_hi:[1,1,1]
	v_pk_fma_f32 v[16:17], v[4:5], v[190:191], v[16:17] op_sel_hi:[0,1,1]
	v_pk_fma_f32 v[16:17], v[4:5], v[192:193], v[16:17] op_sel:[1,0,0] op_sel_hi:[1,1,1]
	v_pk_mul_f32 v[18:19], v[202:203], v[26:27] op_sel_hi:[1,0]
	v_pk_mul_f32 v[20:21], v[204:205], v[26:27] op_sel_hi:[1,0]
	v_add_f32_dpp v16, v16, v16 quad_perm:[1,0,3,2] row_mask:0xf bank_mask:0xf bound_ctrl:1
	v_add_f32_dpp v17, v17, v17 quad_perm:[1,0,3,2] row_mask:0xf bank_mask:0xf bound_ctrl:1
	v_pk_fma_f32 v[18:19], v[2:3], v[194:195], v[18:19]
	v_add_f32_dpp v16, v16, v16 quad_perm:[2,3,0,1] row_mask:0xf bank_mask:0xf bound_ctrl:1
	v_add_f32_dpp v17, v17, v17 quad_perm:[2,3,0,1] row_mask:0xf bank_mask:0xf bound_ctrl:1
	v_pk_fma_f32 v[20:21], v[4:5], v[196:197], v[20:21]
	v_add_f32_dpp v16, v16, v16 row_half_mirror row_mask:0xf bank_mask:0xf bound_ctrl:1
	v_add_f32_dpp v17, v17, v17 row_half_mirror row_mask:0xf bank_mask:0xf bound_ctrl:1
	s_nop 0
	v_add_f32_dpp v16, v16, v16 row_mirror row_mask:0xf bank_mask:0xf bound_ctrl:1
	v_add_f32_dpp v17, v17, v17 row_mirror row_mask:0xf bank_mask:0xf bound_ctrl:1
	v_pk_fma_f32 v[2:3], v[198:199], v[16:17], v[18:19] op_sel_hi:[1,0,1]
	v_pk_fma_f32 v[4:5], v[200:201], v[16:17], v[20:21] op_sel_hi:[1,0,1]
	v_fmac_f32_e32 v17, v209, v16
	ds_write2_b32 v22, v15, v17 offset0:224 offset1:240
	s_add_i32 s0, s0, 1
	s_cmpk_lg_i32 s0, 0x80
	s_waitcnt lgkmcnt(0)
	s_barrier
	s_cbranch_scc1 .LBB0_726
